# NA attention: Q-tile loads and gate loads issued together instead of serial round trips
# speedup vs baseline: 1.0213x; 1.0213x over previous
.LBB0_182:
	ds_bpermute_b32 v0, v186, v10
	v_add_lshl_u32 v22, s25, v89, 10
	v_or3_b32 v232, s24, v80, v22
	v_mov_b32_e32 v233, 0
	v_lshl_add_u64 v[234:235], v[232:233], 1, s[76:77]
	global_load_dwordx4 v[216:219], v[234:235], off
	v_or_b32_e32 v232, 32, v232
	v_lshl_add_u64 v[234:235], v[232:233], 1, s[76:77]
	global_load_dwordx4 v[220:223], v[234:235], off
	v_add_u32_e32 v232, v22, v105
	v_or_b32_e32 v232, s24, v232
	v_lshl_add_u64 v[234:235], v[232:233], 1, s[76:77]
	global_load_dwordx4 v[224:227], v[234:235], off
	v_or_b32_e32 v232, 32, v232
	v_lshl_add_u64 v[234:235], v[232:233], 1, s[76:77]
	global_load_dwordx4 v[228:231], v[234:235], off
	s_add_i32 s23, s23, s34
	s_cmp_ge_i32 s23, s35
	s_waitcnt lgkmcnt(0)
	v_add_f32_e32 v0, v10, v0
	ds_bpermute_b32 v10, v187, v0
	s_waitcnt lgkmcnt(0)
	v_add_f32_e32 v0, v0, v10
	v_rcp_f32_e32 v18, v0
	v_or3_b32 v0, s24, v80, v22
	v_lshlrev_b64 v[14:15], 1, v[0:1]
	v_lshl_add_u64 v[10:11], s[76:77], 0, v[14:15]
	v_pk_mul_f32 v[20:21], v[58:59], v[18:19] op_sel_hi:[1,0]
	v_pk_mul_f32 v[16:17], v[60:61], v[18:19] op_sel_hi:[1,0]
	v_pk_mul_f32 v[26:27], v[66:67], v[18:19] op_sel_hi:[1,0]
	v_pk_mul_f32 v[24:25], v[68:69], v[18:19] op_sel_hi:[1,0]
	v_lshl_add_u64 v[14:15], s[94:95], 0, v[14:15]
	v_or_b32_e32 v0, 32, v0
	s_waitcnt vmcnt(3) lgkmcnt(0)
	v_mov_b32_e32 v10, v216
	v_mov_b32_e32 v11, v217
	v_mov_b32_e32 v12, v218
	v_mov_b32_e32 v13, v219
	v_lshlrev_b32_e32 v28, 16, v10
	v_and_b32_e32 v29, 0xffff0000, v10
	v_mul_f32_e32 v10, 0xbfb8aa3b, v28
	v_exp_f32_e32 v10, v10
	s_nop 0
	v_add_f32_e32 v10, 1.0, v10
	v_rcp_f32_e32 v30, v10
	v_mul_f32_e32 v10, 0xbfb8aa3b, v29
	v_exp_f32_e32 v10, v10
	s_nop 0
	v_add_f32_e32 v10, 1.0, v10
	v_rcp_f32_e32 v31, v10
	s_nop 0
	v_pk_mul_f32 v[28:29], v[30:31], v[28:29]
	s_nop 0
	v_pk_mul_f32 v[20:21], v[20:21], v[28:29]
	s_nop 0
	v_cvt_pk_bf16_f32 v10, v20, v21
	v_lshlrev_b32_e32 v20, 16, v11
	v_and_b32_e32 v21, 0xffff0000, v11
	v_mul_f32_e32 v11, 0xbfb8aa3b, v20
	v_exp_f32_e32 v11, v11
	s_nop 0
	v_add_f32_e32 v11, 1.0, v11
	v_rcp_f32_e32 v28, v11
	v_mul_f32_e32 v11, 0xbfb8aa3b, v21
	v_exp_f32_e32 v11, v11
	s_nop 0
	v_add_f32_e32 v11, 1.0, v11
	v_rcp_f32_e32 v29, v11
	s_nop 0
	v_pk_mul_f32 v[20:21], v[28:29], v[20:21]
	s_nop 0
	v_pk_mul_f32 v[16:17], v[16:17], v[20:21]
	s_nop 0
	v_cvt_pk_bf16_f32 v11, v16, v17
	v_lshlrev_b32_e32 v16, 16, v12
	v_and_b32_e32 v17, 0xffff0000, v12
	v_mul_f32_e32 v12, 0xbfb8aa3b, v16
	v_exp_f32_e32 v12, v12
	s_nop 0
	v_add_f32_e32 v12, 1.0, v12
	v_rcp_f32_e32 v20, v12
	v_mul_f32_e32 v12, 0xbfb8aa3b, v17
	v_exp_f32_e32 v12, v12
	s_nop 0
	v_add_f32_e32 v12, 1.0, v12
	v_rcp_f32_e32 v21, v12
	s_nop 0
	v_pk_mul_f32 v[16:17], v[20:21], v[16:17]
	s_nop 0
	v_pk_mul_f32 v[16:17], v[26:27], v[16:17]
	s_nop 0
	v_cvt_pk_bf16_f32 v12, v16, v17
	v_lshlrev_b32_e32 v16, 16, v13
	v_and_b32_e32 v17, 0xffff0000, v13
	v_mul_f32_e32 v13, 0xbfb8aa3b, v16
	v_exp_f32_e32 v13, v13
	s_nop 0
	v_add_f32_e32 v13, 1.0, v13
	v_rcp_f32_e32 v20, v13
	v_mul_f32_e32 v13, 0xbfb8aa3b, v17
	v_exp_f32_e32 v13, v13
	s_nop 0
	v_add_f32_e32 v13, 1.0, v13
	v_rcp_f32_e32 v21, v13
	s_nop 0
	v_pk_mul_f32 v[16:17], v[20:21], v[16:17]
	s_nop 0
	v_pk_mul_f32 v[16:17], v[24:25], v[16:17]
	v_pk_mul_f32 v[24:25], v[50:51], v[18:19] op_sel_hi:[1,0]
	v_cvt_pk_bf16_f32 v13, v16, v17
	global_store_dwordx4 v[14:15], v[10:13], off
	v_pk_mul_f32 v[20:21], v[52:53], v[18:19] op_sel_hi:[1,0]
	v_pk_mul_f32 v[16:17], v[56:57], v[18:19] op_sel_hi:[1,0]
	v_lshl_add_u64 v[10:11], v[0:1], 1, s[76:77]
	v_pk_mul_f32 v[18:19], v[54:55], v[18:19] op_sel_hi:[1,0]
	s_waitcnt vmcnt(3) lgkmcnt(0)
	v_mov_b32_e32 v10, v220
	v_mov_b32_e32 v11, v221
	v_mov_b32_e32 v12, v222
	v_mov_b32_e32 v13, v223
	v_lshlrev_b32_e32 v26, 16, v10
	v_mul_f32_e32 v0, 0xbfb8aa3b, v26
	v_exp_f32_e32 v0, v0
	v_and_b32_e32 v27, 0xffff0000, v10
	v_add_f32_e32 v0, 1.0, v0
	v_rcp_f32_e32 v28, v0
	v_mul_f32_e32 v0, 0xbfb8aa3b, v27
	v_exp_f32_e32 v0, v0
	s_nop 0
	v_add_f32_e32 v0, 1.0, v0
	v_rcp_f32_e32 v29, v0
	s_nop 0
	v_pk_mul_f32 v[26:27], v[28:29], v[26:27]
	s_nop 0
	v_pk_mul_f32 v[24:25], v[24:25], v[26:27]
	s_nop 0
	v_cvt_pk_bf16_f32 v10, v24, v25
	v_lshlrev_b32_e32 v24, 16, v11
	v_mul_f32_e32 v0, 0xbfb8aa3b, v24
	v_exp_f32_e32 v0, v0
	v_and_b32_e32 v25, 0xffff0000, v11
	v_add_f32_e32 v0, 1.0, v0
	v_rcp_f32_e32 v26, v0
	v_mul_f32_e32 v0, 0xbfb8aa3b, v25
	v_exp_f32_e32 v0, v0
	s_nop 0
	v_add_f32_e32 v0, 1.0, v0
	v_rcp_f32_e32 v27, v0
	s_nop 0
	v_pk_mul_f32 v[24:25], v[26:27], v[24:25]
	s_nop 0
	v_pk_mul_f32 v[20:21], v[20:21], v[24:25]
	s_nop 0
	v_cvt_pk_bf16_f32 v11, v20, v21
	v_lshlrev_b32_e32 v20, 16, v12
	v_mul_f32_e32 v0, 0xbfb8aa3b, v20
	v_exp_f32_e32 v0, v0
	v_and_b32_e32 v21, 0xffff0000, v12
	v_add_f32_e32 v0, 1.0, v0
	v_rcp_f32_e32 v24, v0
	v_mul_f32_e32 v0, 0xbfb8aa3b, v21
	v_exp_f32_e32 v0, v0
	s_nop 0
	v_add_f32_e32 v0, 1.0, v0
	v_rcp_f32_e32 v25, v0
	s_nop 0
	v_pk_mul_f32 v[20:21], v[24:25], v[20:21]
	s_nop 0
	v_pk_mul_f32 v[18:19], v[18:19], v[20:21]
	s_nop 0
	v_cvt_pk_bf16_f32 v12, v18, v19
	v_lshlrev_b32_e32 v18, 16, v13
	v_mul_f32_e32 v0, 0xbfb8aa3b, v18
	v_exp_f32_e32 v0, v0
	v_and_b32_e32 v19, 0xffff0000, v13
	v_add_f32_e32 v0, 1.0, v0
	v_rcp_f32_e32 v20, v0
	v_mul_f32_e32 v0, 0xbfb8aa3b, v19
	v_exp_f32_e32 v0, v0
	s_nop 0
	v_add_f32_e32 v0, 1.0, v0
	v_rcp_f32_e32 v21, v0
	ds_bpermute_b32 v0, v186, v76
	v_pk_mul_f32 v[18:19], v[20:21], v[18:19]
	s_nop 0
	v_pk_mul_f32 v[16:17], v[16:17], v[18:19]
	s_waitcnt lgkmcnt(0)
	v_add_f32_e32 v0, v76, v0
	v_cvt_pk_bf16_f32 v13, v16, v17
	global_store_dwordx4 v[14:15], v[10:13], off offset:64
	ds_bpermute_b32 v10, v187, v0
	s_waitcnt lgkmcnt(0)
	v_add_f32_e32 v0, v0, v10
	v_rcp_f32_e32 v16, v0
	v_add_u32_e32 v0, v22, v105
	v_or_b32_e32 v0, s24, v0
	v_lshlrev_b64 v[14:15], 1, v[0:1]
	v_lshl_add_u64 v[10:11], s[76:77], 0, v[14:15]
	v_pk_mul_f32 v[20:21], v[42:43], v[16:17] op_sel_hi:[1,0]
	v_pk_mul_f32 v[18:19], v[44:45], v[16:17] op_sel_hi:[1,0]
	v_pk_mul_f32 v[24:25], v[46:47], v[16:17] op_sel_hi:[1,0]
	v_pk_mul_f32 v[22:23], v[48:49], v[16:17] op_sel_hi:[1,0]
	v_lshl_add_u64 v[14:15], s[94:95], 0, v[14:15]
	v_or_b32_e32 v0, 32, v0
	v_pk_mul_f32 v[4:5], v[4:5], v[16:17] op_sel_hi:[1,0]
	v_pk_mul_f32 v[2:3], v[2:3], v[16:17] op_sel_hi:[1,0]
	v_pk_mul_f32 v[8:9], v[8:9], v[16:17] op_sel_hi:[1,0]
	v_pk_mul_f32 v[6:7], v[6:7], v[16:17] op_sel_hi:[1,0]
	s_waitcnt vmcnt(3) lgkmcnt(0)
	v_mov_b32_e32 v10, v224
	v_mov_b32_e32 v11, v225
	v_mov_b32_e32 v12, v226
	v_mov_b32_e32 v13, v227
	v_lshlrev_b32_e32 v26, 16, v10
	v_and_b32_e32 v27, 0xffff0000, v10
	v_mul_f32_e32 v10, 0xbfb8aa3b, v26
	v_exp_f32_e32 v10, v10
	s_nop 0
	v_add_f32_e32 v10, 1.0, v10
	v_rcp_f32_e32 v28, v10
	v_mul_f32_e32 v10, 0xbfb8aa3b, v27
	v_exp_f32_e32 v10, v10
	s_nop 0
	v_add_f32_e32 v10, 1.0, v10
	v_rcp_f32_e32 v29, v10
	s_nop 0
	v_pk_mul_f32 v[26:27], v[28:29], v[26:27]
	s_nop 0
	v_pk_mul_f32 v[20:21], v[20:21], v[26:27]
	s_nop 0
	v_cvt_pk_bf16_f32 v10, v20, v21
	v_lshlrev_b32_e32 v20, 16, v11
	v_and_b32_e32 v21, 0xffff0000, v11
	v_mul_f32_e32 v11, 0xbfb8aa3b, v20
	v_exp_f32_e32 v11, v11
	s_nop 0
	v_add_f32_e32 v11, 1.0, v11
	v_rcp_f32_e32 v26, v11
	v_mul_f32_e32 v11, 0xbfb8aa3b, v21
	v_exp_f32_e32 v11, v11
	s_nop 0
	v_add_f32_e32 v11, 1.0, v11
	v_rcp_f32_e32 v27, v11
	s_nop 0
	v_pk_mul_f32 v[20:21], v[26:27], v[20:21]
	s_nop 0
	v_pk_mul_f32 v[18:19], v[18:19], v[20:21]
	s_nop 0
	v_cvt_pk_bf16_f32 v11, v18, v19
	v_lshlrev_b32_e32 v18, 16, v12
	v_and_b32_e32 v19, 0xffff0000, v12
	v_mul_f32_e32 v12, 0xbfb8aa3b, v18
	v_exp_f32_e32 v12, v12
	s_nop 0
	v_add_f32_e32 v12, 1.0, v12
	v_rcp_f32_e32 v20, v12
	v_mul_f32_e32 v12, 0xbfb8aa3b, v19
	v_exp_f32_e32 v12, v12
	s_nop 0
	v_add_f32_e32 v12, 1.0, v12
	v_rcp_f32_e32 v21, v12
	s_nop 0
	v_pk_mul_f32 v[18:19], v[20:21], v[18:19]
	s_nop 0
	v_pk_mul_f32 v[18:19], v[24:25], v[18:19]
	s_nop 0
	v_cvt_pk_bf16_f32 v12, v18, v19
	v_lshlrev_b32_e32 v18, 16, v13
	v_and_b32_e32 v19, 0xffff0000, v13
	v_mul_f32_e32 v13, 0xbfb8aa3b, v18
	v_exp_f32_e32 v13, v13
	s_nop 0
	v_add_f32_e32 v13, 1.0, v13
	v_rcp_f32_e32 v20, v13
	v_mul_f32_e32 v13, 0xbfb8aa3b, v19
	v_exp_f32_e32 v13, v13
	s_nop 0
	v_add_f32_e32 v13, 1.0, v13
	v_rcp_f32_e32 v21, v13
	s_nop 0
	v_pk_mul_f32 v[18:19], v[20:21], v[18:19]
	s_nop 0
	v_pk_mul_f32 v[18:19], v[22:23], v[18:19]
	s_nop 0
	v_cvt_pk_bf16_f32 v13, v18, v19
	global_store_dwordx4 v[14:15], v[10:13], off
	s_nop 1
	v_lshl_add_u64 v[10:11], v[0:1], 1, s[76:77]
	s_waitcnt vmcnt(3) lgkmcnt(0)
	v_mov_b32_e32 v10, v228
	v_mov_b32_e32 v11, v229
	v_mov_b32_e32 v12, v230
	v_mov_b32_e32 v13, v231
	v_lshlrev_b32_e32 v16, 16, v10
	v_mul_f32_e32 v0, 0xbfb8aa3b, v16
	v_exp_f32_e32 v0, v0
	v_and_b32_e32 v17, 0xffff0000, v10
	v_lshlrev_b32_e32 v10, 16, v11
	v_and_b32_e32 v11, 0xffff0000, v11
	v_add_f32_e32 v0, 1.0, v0
	v_rcp_f32_e32 v18, v0
	v_mul_f32_e32 v0, 0xbfb8aa3b, v17
	v_exp_f32_e32 v0, v0
	s_nop 0
	v_add_f32_e32 v0, 1.0, v0
	v_rcp_f32_e32 v19, v0
	v_mul_f32_e32 v0, 0xbfb8aa3b, v10
	v_exp_f32_e32 v0, v0
	v_pk_mul_f32 v[16:17], v[18:19], v[16:17]
	s_nop 0
	v_pk_mul_f32 v[2:3], v[2:3], v[16:17]
	v_add_f32_e32 v0, 1.0, v0
	v_rcp_f32_e32 v16, v0
	v_mul_f32_e32 v0, 0xbfb8aa3b, v11
	v_exp_f32_e32 v0, v0
	v_cvt_pk_bf16_f32 v2, v2, v3
	v_add_f32_e32 v0, 1.0, v0
	v_rcp_f32_e32 v17, v0
	s_nop 0
	v_pk_mul_f32 v[10:11], v[16:17], v[10:11]
	s_nop 0
	v_pk_mul_f32 v[4:5], v[4:5], v[10:11]
	s_nop 0
	v_cvt_pk_bf16_f32 v3, v4, v5
	v_lshlrev_b32_e32 v4, 16, v12
	v_mul_f32_e32 v0, 0xbfb8aa3b, v4
	v_exp_f32_e32 v0, v0
	v_and_b32_e32 v5, 0xffff0000, v12
	v_add_f32_e32 v0, 1.0, v0
	v_rcp_f32_e32 v10, v0
	v_mul_f32_e32 v0, 0xbfb8aa3b, v5
	v_exp_f32_e32 v0, v0
	s_nop 0
	v_add_f32_e32 v0, 1.0, v0
	v_rcp_f32_e32 v11, v0
	s_nop 0
	v_pk_mul_f32 v[4:5], v[10:11], v[4:5]
	s_nop 0
	v_pk_mul_f32 v[4:5], v[6:7], v[4:5]
	v_lshlrev_b32_e32 v6, 16, v13
	v_mul_f32_e32 v0, 0xbfb8aa3b, v6
	v_exp_f32_e32 v0, v0
	v_and_b32_e32 v7, 0xffff0000, v13
	v_cvt_pk_bf16_f32 v4, v4, v5
	v_add_f32_e32 v0, 1.0, v0
	v_rcp_f32_e32 v10, v0
	v_mul_f32_e32 v0, 0xbfb8aa3b, v7
	v_exp_f32_e32 v0, v0
	s_nop 0
	v_add_f32_e32 v0, 1.0, v0
	v_rcp_f32_e32 v11, v0
	s_nop 0
	v_pk_mul_f32 v[6:7], v[10:11], v[6:7]
	s_nop 0
	v_pk_mul_f32 v[6:7], v[8:9], v[6:7]
	s_nop 0
	v_cvt_pk_bf16_f32 v5, v6, v7
	global_store_dwordx4 v[14:15], v[2:5], off offset:64
	s_cbranch_scc1 .LBB0_220

.LBB0_193:
	s_or_b64 exec, exec, s[0:1]
	s_mul_i32 s0, s4, s21
	s_sub_i32 s1, s23, s0
	s_lshl_b32 s0, s1, 1
	s_max_i32 s6, s0, 4
	s_add_i32 s6, s6, -4
	s_min_u32 s80, s6, 24
	s_max_i32 s6, s0, 3
	s_add_i32 s6, s6, -3
	s_min_u32 s6, s6, 24
	s_ashr_i32 s7, s4, 4
	s_add_i32 s6, s6, 7
	s_cmp_lt_i32 s1, 16
	s_movk_i32 s8, 0xf800
	s_cselect_b32 s81, s80, 0
	s_cselect_b32 s6, s6, -1
	s_cselect_b32 s8, 0x100, s8
	s_lshl_b32 s1, s1, 7
	s_sub_i32 s82, s6, s81
	s_mul_i32 s6, s7, 0x900
	s_add_i32 s25, s8, s1
	s_add_i32 s25, s25, s6
	s_lshl_b32 s24, s5, 6
	v_or_b32_e32 v6, s24, v90
	v_add_u32_e32 v0, s25, v101
	v_lshl_or_b32 v0, v0, 10, v6
	v_lshl_add_u64 v[2:3], v[0:1], 1, s[26:27]
	global_load_dwordx4 v[200:203], v[2:3], off
	v_add_u32_e32 v0, s25, v102
	v_lshl_or_b32 v0, v0, 10, v6
	v_lshl_add_u64 v[2:3], v[0:1], 1, s[26:27]
	global_load_dwordx4 v[204:207], v[2:3], off
	v_add_u32_e32 v0, s25, v103
	v_lshl_or_b32 v0, v0, 10, v6
	v_lshl_add_u64 v[2:3], v[0:1], 1, s[26:27]
	global_load_dwordx4 v[208:211], v[2:3], off
	v_add_u32_e32 v0, s25, v104
	v_lshl_or_b32 v0, v0, 10, v6
	v_lshl_add_u64 v[2:3], v[0:1], 1, s[26:27]
	global_load_dwordx4 v[212:215], v[2:3], off
	s_lshl_b32 s1, s81, 6
	s_not_b32 s5, s82
	s_addk_i32 s1, 0x100
	s_lshl_b32 s5, s5, 6
	s_cmp_lt_i32 s82, 0
	s_cselect_b32 s5, s5, s1
	v_add_u32_e32 v122, s6, v91
	v_readfirstlane_b32 s1, v94
	s_mov_b32 m0, s1
	s_lshl_b32 s1, s7, 10
	s_or_b32 s7, s24, s1
	v_add_u32_e32 v123, s6, v98
	s_mov_b32 s83, 0
	s_cmp_gt_i32 s82, -5
	v_add_lshl_u32 v0, s5, v122, 10
	v_or3_b32 v0, v0, s24, v92
	v_lshl_add_u64 v[2:3], v[0:1], 1, s[28:29]
	v_add_u32_e32 v0, s7, v97
	v_mul_lo_u32 v0, v0, s96
	v_or_b32_e32 v0, v0, v92
	v_add_u32_e32 v0, s5, v0
	global_load_lds_dwordx4 v[2:3], off
	v_lshl_add_u64 v[2:3], v[0:1], 1, s[58:59]
	v_add_u32_e32 v0, 0x2000, v94
	s_nop 0
	v_readfirstlane_b32 s8, v0
	v_add_lshl_u32 v0, s5, v123, 10
	s_mov_b32 m0, s8
	v_or3_b32 v0, v0, s24, v99
	global_load_lds_dwordx4 v[2:3], off
	v_lshl_add_u64 v[2:3], v[0:1], 1, s[28:29]
	v_add_u32_e32 v0, 0x400, v94
	s_nop 0
	v_readfirstlane_b32 s6, v0
	v_add_u32_e32 v0, s7, v100
	v_mul_lo_u32 v0, v0, s96
	v_or_b32_e32 v124, v0, v99
	s_mov_b32 m0, s6
	v_add_u32_e32 v0, s5, v124
	global_load_lds_dwordx4 v[2:3], off
	v_lshl_add_u64 v[2:3], v[0:1], 1, s[58:59]
	v_add_u32_e32 v0, 0x2400, v94
	s_nop 0
	v_readfirstlane_b32 s5, v0
	s_mov_b32 m0, s5
	s_nop 0
	global_load_lds_dwordx4 v[2:3], off
	s_waitcnt vmcnt(4)
	ds_write_b128 v118, v[200:203] offset:32768
	ds_write_b128 v119, v[204:207] offset:32768
	ds_write_b128 v120, v[208:211] offset:32768
	ds_write_b128 v121, v[212:215] offset:32768
	s_waitcnt vmcnt(0) lgkmcnt(0)
	s_barrier
	s_cbranch_scc0 .LBB0_181
	s_or_b32 s0, s0, 1
	s_max_i32 s0, s0, 4
	s_add_i32 s0, s0, -4
	s_min_u32 s56, s0, 24
	s_mul_i32 s0, s62, s4
	v_or_b32_e32 v0, s1, v95
	s_add_i32 s0, s81, s0
	s_lshl_b32 s1, s23, 1
	s_sub_i32 s0, s0, s1
	s_mul_i32 s1, s21, 0xf8
	v_add3_u32 v0, v96, s24, v0
	s_mul_i32 s1, s1, s4
	s_mul_i32 s4, s81, 0x7c
	v_mul_lo_u32 v0, v0, s96
	s_add_i32 s1, s1, s4
	s_mul_i32 s4, s23, 0xf8
	v_mov_b32_e32 v12, v1
	v_mov_b32_e32 v13, v1
	v_or_b32_e32 v125, v0, v92
	s_mulk_i32 s0, 0x7c
	s_sub_i32 s1, s1, s4
	v_mov_b32_e32 v0, v1
	v_mov_b32_e32 v10, v1
	v_mov_b32_e32 v11, v1
	v_mov_b32_e32 v74, 0xe0ad78ec
	v_mov_b64_e32 v[20:21], v[12:13]
	v_mov_b64_e32 v[28:29], v[12:13]
	v_mov_b64_e32 v[32:33], v[12:13]
	v_mov_b64_e32 v[16:17], v[12:13]
	v_mov_b64_e32 v[24:25], v[12:13]
	v_mov_b64_e32 v[36:37], v[12:13]
	v_mov_b64_e32 v[40:41], v[12:13]
	s_add_i32 s88, s82, 1
	s_add_i32 s89, s80, 8
	s_add_i32 s57, s56, 8
	s_add_i32 s22, s82, 4
	s_add_i32 s96, s82, 5
	v_or_b32_e32 v126, s24, v92
	v_or_b32_e32 v127, s24, v99
	s_add_i32 s97, s0, 0x103e0
	v_add_u32_e32 v128, s1, v115
	s_add_i32 s98, s0, 0x103e4
	s_add_i32 s99, s0, 0x103e8
	s_add_i32 s30, s0, 0x103ec
	s_add_i32 s4, s0, 0x10420
	v_mov_b64_e32 v[18:19], v[10:11]
	v_mov_b64_e32 v[26:27], v[10:11]
	v_mov_b64_e32 v[30:31], v[10:11]
	v_mov_b64_e32 v[14:15], v[10:11]
	v_mov_b64_e32 v[22:23], v[10:11]
	v_mov_b64_e32 v[34:35], v[10:11]
	v_mov_b64_e32 v[38:39], v[10:11]
	s_mov_b32 s8, 0
	v_mov_b64_e32 v[78:79], v[0:1]
	v_mov_b32_e32 v75, v74
